# GEMM K-loop: per-iteration first-iteration test removed (unit entry falls straight into the peeled first iteration); on top of m13
# speedup vs baseline: 1.0086x; 1.0033x over previous
; #define SNEXT(i, u) sched_next(i, u, p.G, p.c, p.total, p.mode, p.nM0, p.nN0, p.A0, p.B0, p.A1, p.B1, p.A2, p.B2, p.A3, p.B3)
; __device__ __forceinline__ void gemm_phase(LAS unsigned char* lds, const GP p, const int tid) {
;     ...
;         const bool has_next = SNEXT(ui + 1, nxt);
;         const char* nA = has_next ? APTR(nxt) : cA; const char* nB = has_next ? BPTR(nxt) : cB;
;         for (int t = 0; t < nt; t += 2) {
;             const bool last = (t == nt - 2);
;             if (last && p.mode != 1) {
;                 const float* rp = p.rs + cur.pm * BM + wr * 64 + fr;
; #pragma unroll
;                 for (int ai = 0; ai < 2; ++ai)
; #pragma unroll
;                     for (int m = 0; m < 4; ++m) rsv[ai][m] = rp[ai * HALF + m * 16];
;             }
;             const char* a1 = cA + (size_t)(t + 1) * kstep;
;             const char* a2 = last ? nA : cA + (size_t)(t + 2) * kstep; const char* b2 = last ? nB : cB + (size_t)(t + 2) * kstep;
.LBB0_103:
	s_lshl_b32 s42, s80, 8
	s_ashr_i32 s43, s42, 31
	s_add_u32 s82, s82, 0x80
	s_addc_u32 s83, s83, 0
	s_add_u32 s81, s84, 0x100
	s_addc_u32 s91, s85, 0
	s_mov_b32 s98, 0
	v_lshl_add_u64 v[128:129], s[42:43], 2, v[154:155]
	s_mov_b64 s[84:85], 0

; #define PG8_STAGE(bufoff, gbase, voff) do { _Pragma("unroll") for (int _i = 0; _i < 2; ++_i) \
;         __builtin_amdgcn_global_load_lds((const unsigned*)((const char*)(gbase) + (voff)[_i]), (LAS unsigned*)(lds + (bufoff) + ldsw + _i * 8192), 16, 0, 0); } while (0)
; #define PG8_LDA(dst, b, h) do { _Pragma("unroll") for (int m = 0; m < 4; ++m) _Pragma("unroll") for (int k = 0; k < 2; ++k) dst[m][k] = *(const LAS bf16x8*)(lds + PG8_SA(b, h) + aoff + m * 2048 + k * 1024); } while (0)
; #define PG8_LDB(dst, b, h) do { _Pragma("unroll") for (int n = 0; n < 2; ++n) _Pragma("unroll") for (int k = 0; k < 2; ++k) dst[n][k] = *(const LAS bf16x8*)(lds + PG8_SB(b, h) + boff + n * 2048 + k * 1024); } while (0)
; #define PG8_MMA(ai, bj, At, Bt) do { __builtin_amdgcn_s_setprio(1); _Pragma("unroll") for (int m = 0; m < 4; ++m) _Pragma("unroll") for (int n = 0; n < 2; ++n) _Pragma("unroll") for (int k = 0; k < 2; ++k) \
;         acc[ai][bj][m][n] = __builtin_amdgcn_mfma_f32_16x16x32_bf16(Bt[n][k], At[m][k], acc[ai][bj][m][n], 0, 0, 0); __builtin_amdgcn_s_setprio(0); } while (0)
; #define PG8_BAR __builtin_amdgcn_s_barrier()
; __device__ __forceinline__ void gemm_phase(LAS unsigned char* lds, const GP p, const int tid) {
;     ...
;         for (int t = 0; t < nt; t += 2) {
;             const bool last = (t == nt - 2);
;             if (last && p.mode != 1) {
;                 const float* rp = p.rs + cur.pm * BM + wr * 64 + fr;
; #pragma unroll
;                 for (int ai = 0; ai < 2; ++ai)
; #pragma unroll
;                     for (int m = 0; m < 4; ++m) rsv[ai][m] = rp[ai * HALF + m * 16];
;             }
;             const char* a1 = cA + (size_t)(t + 1) * kstep;
;             const char* a2 = last ? nA : cA + (size_t)(t + 2) * kstep; const char* b2 = last ? nB : cB + (size_t)(t + 2) * kstep;
;             const char* a3 = a2 + kstep; const char* b3 = b2 + kstep;
;             PG8_LDB(B0, 0, 0); PG8_LDB(B1, 0, 1); PG8_SCHED; PG8_LDA(At, 0, 0); PG8_STAGE(PG8_SA(1, 1), a1 + hstep, voffA);
;             PG8_WAIT_V(8); PG8_WAIT_L(0); PG8_BAR; PG8_MMA(0, 0, At, B0); PG8_MMA(0, 1, At, B1); PG8_BAR; PG8_SCHED;
;             PG8_LDA(At, 0, 1); PG8_STAGE(PG8_SB(0, 0), b2, voffB); PG8_STAGE(PG8_SB(0, 1), b2 + hstep, voffB); PG8_STAGE(PG8_SA(0, 0), a2, voffA);
;             PG8_WAIT_V(8); PG8_WAIT_L(0); PG8_BAR; PG8_MMA(1, 0, At, B0); PG8_MMA(1, 1, At, B1); PG8_BAR; PG8_SCHED;
.LBB0_104:
	s_add_i32 s98, s98, 2
	s_add_u32 s43, s82, 0x80
	s_addc_u32 s99, s83, 0
	s_and_b64 s[86:87], s[84:85], exec
	s_cselect_b32 s87, s77, s99
	s_cselect_b32 s86, s76, s43
	s_add_i32 s43, 0, 0x10000
	s_and_b64 s[84:85], s[84:85], exec
	s_cselect_b32 s85, s79, s91
	s_cselect_b32 s84, s78, s81
	s_add_i32 s99, 0, 0x14000
	ds_read_b128 v[130:133], v238
	ds_read_b128 v[134:137], v238 offset:1024
	ds_read_b128 v[138:141], v238 offset:2048
	ds_read_b128 v[180:183], v238 offset:3072
	ds_read_b128 v[184:187], v239
	ds_read_b128 v[188:191], v239 offset:1024
	ds_read_b128 v[192:195], v239 offset:2048
	ds_read_b128 v[196:199], v239 offset:3072
	s_add_i32 m0, s53, 0xc000
	ds_read_b128 v[200:203], v167
	ds_read_b128 v[204:207], v167 offset:1024
	ds_read_b128 v[208:211], v167 offset:2048
	ds_read_b128 v[218:221], v167 offset:3072
	ds_read_b128 v[222:225], v167 offset:4096
	ds_read_b128 v[226:229], v167 offset:5120
	ds_read_b128 v[230:233], v167 offset:6144
	ds_read_b128 v[234:237], v167 offset:7168
	global_load_lds_dwordx4 v160, s[82:83]
	s_add_i32 m0, s53, 0xe000
	s_nop 0
	global_load_lds_dwordx4 v162, s[82:83]
	s_waitcnt vmcnt(8)
	s_waitcnt lgkmcnt(0)
	s_barrier
	s_setprio 1
	v_mfma_f32_16x16x32_bf16 v[124:127], v[130:133], v[200:203], v[124:127]
	v_mfma_f32_16x16x32_bf16 v[120:123], v[138:141], v[200:203], v[120:123]
	v_mfma_f32_16x16x32_bf16 v[108:111], v[130:133], v[208:211], v[108:111]
	v_mfma_f32_16x16x32_bf16 v[104:107], v[138:141], v[208:211], v[104:107]
	v_mfma_f32_16x16x32_bf16 v[92:95], v[130:133], v[222:225], v[92:95]
	v_mfma_f32_16x16x32_bf16 v[88:91], v[138:141], v[222:225], v[88:91]
	v_mfma_f32_16x16x32_bf16 v[76:79], v[130:133], v[230:233], v[76:79]
	v_mfma_f32_16x16x32_bf16 v[72:75], v[138:141], v[230:233], v[72:75]
	v_mfma_f32_16x16x32_bf16 v[124:127], v[134:137], v[204:207], v[124:127]
	v_mfma_f32_16x16x32_bf16 v[120:123], v[180:183], v[204:207], v[120:123]
	v_mfma_f32_16x16x32_bf16 v[108:111], v[134:137], v[218:221], v[108:111]
	v_mfma_f32_16x16x32_bf16 v[104:107], v[180:183], v[218:221], v[104:107]
	v_mfma_f32_16x16x32_bf16 v[92:95], v[134:137], v[226:229], v[92:95]
	v_mfma_f32_16x16x32_bf16 v[88:91], v[180:183], v[226:229], v[88:91]
	v_mfma_f32_16x16x32_bf16 v[76:79], v[134:137], v[234:237], v[76:79]
	v_mfma_f32_16x16x32_bf16 v[72:75], v[180:183], v[234:237], v[72:75]
	s_setprio 0
	s_setprio 1
	v_mfma_f32_16x16x32_bf16 v[116:119], v[184:187], v[200:203], v[116:119]
	v_mfma_f32_16x16x32_bf16 v[112:115], v[192:195], v[200:203], v[112:115]
	v_mfma_f32_16x16x32_bf16 v[100:103], v[184:187], v[208:211], v[100:103]
	v_mfma_f32_16x16x32_bf16 v[96:99], v[192:195], v[208:211], v[96:99]
	v_mfma_f32_16x16x32_bf16 v[84:87], v[184:187], v[222:225], v[84:87]
	v_mfma_f32_16x16x32_bf16 v[80:83], v[192:195], v[222:225], v[80:83]
	v_mfma_f32_16x16x32_bf16 v[68:71], v[184:187], v[230:233], v[68:71]
	v_mfma_f32_16x16x32_bf16 v[64:67], v[192:195], v[230:233], v[64:67]
	v_mfma_f32_16x16x32_bf16 v[116:119], v[188:191], v[204:207], v[116:119]
	v_mfma_f32_16x16x32_bf16 v[112:115], v[196:199], v[204:207], v[112:115]
	v_mfma_f32_16x16x32_bf16 v[100:103], v[188:191], v[218:221], v[100:103]
	v_mfma_f32_16x16x32_bf16 v[96:99], v[196:199], v[218:221], v[96:99]
	v_mfma_f32_16x16x32_bf16 v[84:87], v[188:191], v[226:229], v[84:87]
	v_mfma_f32_16x16x32_bf16 v[80:83], v[196:199], v[226:229], v[80:83]
	v_mfma_f32_16x16x32_bf16 v[68:71], v[188:191], v[234:237], v[68:71]
	v_mfma_f32_16x16x32_bf16 v[64:67], v[196:199], v[234:237], v[64:67]
	s_setprio 0
	s_barrier
	s_add_i32 s43, s43, s52
	s_mov_b64 s[100:101], s[84:85]
	s_mov_b32 m0, s43
	ds_read_b128 v[200:203], v167 offset:16384
	ds_read_b128 v[204:207], v167 offset:17408
	ds_read_b128 v[208:211], v167 offset:18432
	ds_read_b128 v[218:221], v167 offset:19456
	ds_read_b128 v[222:225], v167 offset:20480
	ds_read_b128 v[226:229], v167 offset:21504
	ds_read_b128 v[230:233], v167 offset:22528
	ds_read_b128 v[234:237], v167 offset:23552
	global_load_lds_dwordx4 v148, s[84:85]
	s_add_i32 m0, s43, 0x2000
	s_add_i32 s43, s99, s52
	global_load_lds_dwordx4 v152, s[84:85]
	s_add_u32 s84, s84, s74
	s_addc_u32 s85, s85, 0
	s_mov_b32 m0, s43
	s_nop 0
	global_load_lds_dwordx4 v148, s[84:85]
	s_add_i32 m0, s43, 0x2000
	s_nop 0
	global_load_lds_dwordx4 v152, s[84:85]
	s_mov_b32 m0, s53
	s_nop 0
	global_load_lds_dwordx4 v146, s[86:87]
	s_mov_b32 m0, s54
	s_nop 0
	global_load_lds_dwordx4 v150, s[86:87]
	s_waitcnt vmcnt(8)
	s_waitcnt lgkmcnt(0)
	s_barrier
	s_setprio 1
	v_mfma_f32_16x16x32_bf16 v[60:63], v[130:133], v[200:203], v[60:63]
	v_mfma_f32_16x16x32_bf16 v[56:59], v[138:141], v[200:203], v[56:59]
	v_mfma_f32_16x16x32_bf16 v[44:47], v[130:133], v[208:211], v[44:47]
	v_mfma_f32_16x16x32_bf16 v[40:43], v[138:141], v[208:211], v[40:43]
	v_mfma_f32_16x16x32_bf16 v[28:31], v[130:133], v[222:225], v[28:31]
	v_mfma_f32_16x16x32_bf16 v[24:27], v[138:141], v[222:225], v[24:27]
	v_mfma_f32_16x16x32_bf16 v[12:15], v[130:133], v[230:233], v[12:15]
	v_mfma_f32_16x16x32_bf16 v[8:11], v[138:141], v[230:233], v[8:11]
	v_mfma_f32_16x16x32_bf16 v[60:63], v[134:137], v[204:207], v[60:63]
	v_mfma_f32_16x16x32_bf16 v[56:59], v[180:183], v[204:207], v[56:59]
	v_mfma_f32_16x16x32_bf16 v[44:47], v[134:137], v[218:221], v[44:47]
	v_mfma_f32_16x16x32_bf16 v[40:43], v[180:183], v[218:221], v[40:43]
	v_mfma_f32_16x16x32_bf16 v[28:31], v[134:137], v[226:229], v[28:31]
	v_mfma_f32_16x16x32_bf16 v[24:27], v[180:183], v[226:229], v[24:27]
	v_mfma_f32_16x16x32_bf16 v[12:15], v[134:137], v[234:237], v[12:15]
	v_mfma_f32_16x16x32_bf16 v[8:11], v[180:183], v[234:237], v[8:11]
	s_setprio 0
	s_setprio 1
	v_mfma_f32_16x16x32_bf16 v[52:55], v[184:187], v[200:203], v[52:55]
	v_mfma_f32_16x16x32_bf16 v[48:51], v[192:195], v[200:203], v[48:51]
	v_mfma_f32_16x16x32_bf16 v[36:39], v[184:187], v[208:211], v[36:39]
	v_mfma_f32_16x16x32_bf16 v[32:35], v[192:195], v[208:211], v[32:35]
	v_mfma_f32_16x16x32_bf16 v[20:23], v[184:187], v[222:225], v[20:23]
	v_mfma_f32_16x16x32_bf16 v[16:19], v[192:195], v[222:225], v[16:19]
	v_mfma_f32_16x16x32_bf16 v[4:7], v[184:187], v[230:233], v[4:7]
	v_mfma_f32_16x16x32_bf16 v[0:3], v[192:195], v[230:233], v[0:3]
	v_mfma_f32_16x16x32_bf16 v[52:55], v[188:191], v[204:207], v[52:55]
	v_mfma_f32_16x16x32_bf16 v[48:51], v[196:199], v[204:207], v[48:51]
	v_mfma_f32_16x16x32_bf16 v[36:39], v[188:191], v[218:221], v[36:39]
	v_mfma_f32_16x16x32_bf16 v[32:35], v[196:199], v[218:221], v[32:35]
	v_mfma_f32_16x16x32_bf16 v[20:23], v[188:191], v[226:229], v[20:23]
	v_mfma_f32_16x16x32_bf16 v[16:19], v[196:199], v[226:229], v[16:19]
	v_mfma_f32_16x16x32_bf16 v[4:7], v[188:191], v[234:237], v[4:7]
	v_mfma_f32_16x16x32_bf16 v[0:3], v[196:199], v[234:237], v[0:3]
	s_setprio 0
	s_barrier
; #define PG8_STAGE(bufoff, gbase, voff) do { _Pragma("unroll") for (int _i = 0; _i < 2; ++_i) \
;         __builtin_amdgcn_global_load_lds((const unsigned*)((const char*)(gbase) + (voff)[_i]), (LAS unsigned*)(lds + (bufoff) + ldsw + _i * 8192), 16, 0, 0); } while (0)
; #define PG8_LDA(dst, b, h) do { _Pragma("unroll") for (int m = 0; m < 4; ++m) _Pragma("unroll") for (int k = 0; k < 2; ++k) dst[m][k] = *(const LAS bf16x8*)(lds + PG8_SA(b, h) + aoff + m * 2048 + k * 1024); } while (0)
; #define PG8_LDB(dst, b, h) do { _Pragma("unroll") for (int n = 0; n < 2; ++n) _Pragma("unroll") for (int k = 0; k < 2; ++k) dst[n][k] = *(const LAS bf16x8*)(lds + PG8_SB(b, h) + boff + n * 2048 + k * 1024); } while (0)
; #define PG8_MMA(ai, bj, At, Bt) do { __builtin_amdgcn_s_setprio(1); _Pragma("unroll") for (int m = 0; m < 4; ++m) _Pragma("unroll") for (int n = 0; n < 2; ++n) _Pragma("unroll") for (int k = 0; k < 2; ++k) \
;         acc[ai][bj][m][n] = __builtin_amdgcn_mfma_f32_16x16x32_bf16(Bt[n][k], At[m][k], acc[ai][bj][m][n], 0, 0, 0); __builtin_amdgcn_s_setprio(0); } while (0)
; #define PG8_WAIT_V(n) asm volatile("s_waitcnt vmcnt(" #n ")" ::: "memory")
; #define PG8_WAIT_L(n) asm volatile("s_waitcnt lgkmcnt(" #n ")" ::: "memory")
; #define PG8_BAR __builtin_amdgcn_s_barrier()
; #define PG8_SCHED __builtin_amdgcn_sched_barrier(0)
; __device__ __forceinline__ void gemm_phase(LAS unsigned char* lds, const GP p, const int tid) {
;     ...
;             PG8_LDB(B0, 1, 0); PG8_LDB(B1, 1, 1); PG8_SCHED; PG8_LDA(At, 1, 0); PG8_STAGE(PG8_SA(0, 1), a2 + hstep, voffA);
;             PG8_WAIT_V(8); PG8_WAIT_L(0); PG8_BAR; PG8_MMA(0, 0, At, B0); PG8_MMA(0, 1, At, B1); PG8_BAR; PG8_SCHED;
;             PG8_LDA(At, 1, 1); PG8_STAGE(PG8_SB(1, 0), b3, voffB); PG8_STAGE(PG8_SB(1, 1), b3 + hstep, voffB); PG8_STAGE(PG8_SA(1, 0), a3, voffA);
;             PG8_WAIT_V(8); PG8_WAIT_L(0); PG8_BAR; PG8_MMA(1, 0, At, B0); PG8_MMA(1, 1, At, B1); PG8_BAR; PG8_SCHED;
;         }
	s_add_i32 s43, 0, 0x18000
	s_add_i32 s99, 0, 0x1c000
	ds_read_b128 v[130:133], v240
	ds_read_b128 v[134:137], v240 offset:1024
	ds_read_b128 v[138:141], v240 offset:2048
	ds_read_b128 v[180:183], v240 offset:3072
	ds_read_b128 v[184:187], v241
	ds_read_b128 v[188:191], v241 offset:1024
	ds_read_b128 v[192:195], v241 offset:2048
	ds_read_b128 v[196:199], v241 offset:3072
	s_add_u32 s84, s86, s74
	s_addc_u32 s85, s87, 0
	s_mov_b32 m0, s55
	ds_read_b128 v[200:203], v167 offset:32768
	ds_read_b128 v[204:207], v167 offset:33792
	ds_read_b128 v[208:211], v167 offset:34816
	ds_read_b128 v[218:221], v167 offset:35840
	ds_read_b128 v[222:225], v167 offset:36864
	ds_read_b128 v[226:229], v167 offset:37888
	ds_read_b128 v[230:233], v167 offset:38912
	ds_read_b128 v[234:237], v167 offset:39936
	global_load_lds_dwordx4 v146, s[84:85]
	s_mov_b32 m0, s56
	s_nop 0
	global_load_lds_dwordx4 v150, s[84:85]
	s_waitcnt vmcnt(8)
	s_waitcnt lgkmcnt(0)
	s_barrier
	s_setprio 1
	v_mfma_f32_16x16x32_bf16 v[124:127], v[130:133], v[200:203], v[124:127]
	v_mfma_f32_16x16x32_bf16 v[120:123], v[138:141], v[200:203], v[120:123]
	v_mfma_f32_16x16x32_bf16 v[108:111], v[130:133], v[208:211], v[108:111]
	v_mfma_f32_16x16x32_bf16 v[104:107], v[138:141], v[208:211], v[104:107]
	v_mfma_f32_16x16x32_bf16 v[92:95], v[130:133], v[222:225], v[92:95]
	v_mfma_f32_16x16x32_bf16 v[88:91], v[138:141], v[222:225], v[88:91]
	v_mfma_f32_16x16x32_bf16 v[76:79], v[130:133], v[230:233], v[76:79]
	v_mfma_f32_16x16x32_bf16 v[72:75], v[138:141], v[230:233], v[72:75]
	v_mfma_f32_16x16x32_bf16 v[124:127], v[134:137], v[204:207], v[124:127]
	v_mfma_f32_16x16x32_bf16 v[120:123], v[180:183], v[204:207], v[120:123]
	v_mfma_f32_16x16x32_bf16 v[108:111], v[134:137], v[218:221], v[108:111]
	v_mfma_f32_16x16x32_bf16 v[104:107], v[180:183], v[218:221], v[104:107]
	v_mfma_f32_16x16x32_bf16 v[92:95], v[134:137], v[226:229], v[92:95]
	v_mfma_f32_16x16x32_bf16 v[88:91], v[180:183], v[226:229], v[88:91]
	v_mfma_f32_16x16x32_bf16 v[76:79], v[134:137], v[234:237], v[76:79]
	v_mfma_f32_16x16x32_bf16 v[72:75], v[180:183], v[234:237], v[72:75]
	s_setprio 0
	s_setprio 1
	v_mfma_f32_16x16x32_bf16 v[116:119], v[184:187], v[200:203], v[116:119]
	v_mfma_f32_16x16x32_bf16 v[112:115], v[192:195], v[200:203], v[112:115]
	v_mfma_f32_16x16x32_bf16 v[100:103], v[184:187], v[208:211], v[100:103]
	v_mfma_f32_16x16x32_bf16 v[96:99], v[192:195], v[208:211], v[96:99]
	v_mfma_f32_16x16x32_bf16 v[84:87], v[184:187], v[222:225], v[84:87]
	v_mfma_f32_16x16x32_bf16 v[80:83], v[192:195], v[222:225], v[80:83]
	v_mfma_f32_16x16x32_bf16 v[68:71], v[184:187], v[230:233], v[68:71]
	v_mfma_f32_16x16x32_bf16 v[64:67], v[192:195], v[230:233], v[64:67]
	v_mfma_f32_16x16x32_bf16 v[116:119], v[188:191], v[204:207], v[116:119]
	v_mfma_f32_16x16x32_bf16 v[112:115], v[196:199], v[204:207], v[112:115]
	v_mfma_f32_16x16x32_bf16 v[100:103], v[188:191], v[218:221], v[100:103]
	v_mfma_f32_16x16x32_bf16 v[96:99], v[196:199], v[218:221], v[96:99]
	v_mfma_f32_16x16x32_bf16 v[84:87], v[188:191], v[226:229], v[84:87]
	v_mfma_f32_16x16x32_bf16 v[80:83], v[196:199], v[226:229], v[80:83]
	v_mfma_f32_16x16x32_bf16 v[68:71], v[188:191], v[234:237], v[68:71]
	v_mfma_f32_16x16x32_bf16 v[64:67], v[196:199], v[234:237], v[64:67]
	s_setprio 0
	s_barrier
	s_add_i32 s43, s43, s52
	s_add_u32 s100, s100, 0x80
	s_addc_u32 s101, s101, 0
	s_mov_b32 m0, s43
	ds_read_b128 v[200:203], v167 offset:49152
	ds_read_b128 v[204:207], v167 offset:50176
	ds_read_b128 v[208:211], v167 offset:51200
	ds_read_b128 v[218:221], v167 offset:52224
	ds_read_b128 v[222:225], v167 offset:53248
	ds_read_b128 v[226:229], v167 offset:54272
	ds_read_b128 v[230:233], v167 offset:55296
	ds_read_b128 v[234:237], v167 offset:56320
	global_load_lds_dwordx4 v148, s[100:101]
	s_add_i32 m0, s43, 0x2000
	s_add_i32 s43, s99, s52
	global_load_lds_dwordx4 v152, s[100:101]
	s_add_u32 s100, s100, s74
	s_addc_u32 s101, s101, 0
	s_mov_b32 m0, s43
	s_nop 0
	global_load_lds_dwordx4 v148, s[100:101]
	s_add_u32 s86, s86, 0x80
	s_addc_u32 s87, s87, 0
	s_add_i32 m0, s43, 0x2000
	s_nop 0
	global_load_lds_dwordx4 v152, s[100:101]
	s_mov_b32 m0, s57
	s_nop 0
	global_load_lds_dwordx4 v146, s[86:87]
	s_mov_b32 m0, s58
	s_nop 0
	global_load_lds_dwordx4 v150, s[86:87]
	s_waitcnt vmcnt(8)
	s_waitcnt lgkmcnt(0)
	s_barrier
	s_setprio 1
	v_mfma_f32_16x16x32_bf16 v[60:63], v[130:133], v[200:203], v[60:63]
	v_mfma_f32_16x16x32_bf16 v[56:59], v[138:141], v[200:203], v[56:59]
	v_mfma_f32_16x16x32_bf16 v[44:47], v[130:133], v[208:211], v[44:47]
	v_mfma_f32_16x16x32_bf16 v[40:43], v[138:141], v[208:211], v[40:43]
	v_mfma_f32_16x16x32_bf16 v[28:31], v[130:133], v[222:225], v[28:31]
	v_mfma_f32_16x16x32_bf16 v[24:27], v[138:141], v[222:225], v[24:27]
	v_mfma_f32_16x16x32_bf16 v[12:15], v[130:133], v[230:233], v[12:15]
	v_mfma_f32_16x16x32_bf16 v[8:11], v[138:141], v[230:233], v[8:11]
	v_mfma_f32_16x16x32_bf16 v[60:63], v[134:137], v[204:207], v[60:63]
	v_mfma_f32_16x16x32_bf16 v[56:59], v[180:183], v[204:207], v[56:59]
	v_mfma_f32_16x16x32_bf16 v[44:47], v[134:137], v[218:221], v[44:47]
	v_mfma_f32_16x16x32_bf16 v[40:43], v[180:183], v[218:221], v[40:43]
	v_mfma_f32_16x16x32_bf16 v[28:31], v[134:137], v[226:229], v[28:31]
	v_mfma_f32_16x16x32_bf16 v[24:27], v[180:183], v[226:229], v[24:27]
	v_mfma_f32_16x16x32_bf16 v[12:15], v[134:137], v[234:237], v[12:15]
	v_mfma_f32_16x16x32_bf16 v[8:11], v[180:183], v[234:237], v[8:11]
	s_setprio 0
	s_setprio 1
	v_mfma_f32_16x16x32_bf16 v[52:55], v[184:187], v[200:203], v[52:55]
	v_mfma_f32_16x16x32_bf16 v[48:51], v[192:195], v[200:203], v[48:51]
	v_mfma_f32_16x16x32_bf16 v[36:39], v[184:187], v[208:211], v[36:39]
	v_mfma_f32_16x16x32_bf16 v[32:35], v[192:195], v[208:211], v[32:35]
	v_mfma_f32_16x16x32_bf16 v[20:23], v[184:187], v[222:225], v[20:23]
	v_mfma_f32_16x16x32_bf16 v[16:19], v[192:195], v[222:225], v[16:19]
	v_mfma_f32_16x16x32_bf16 v[4:7], v[184:187], v[230:233], v[4:7]
	v_mfma_f32_16x16x32_bf16 v[0:3], v[192:195], v[230:233], v[0:3]
	v_mfma_f32_16x16x32_bf16 v[52:55], v[188:191], v[204:207], v[52:55]
	v_mfma_f32_16x16x32_bf16 v[48:51], v[196:199], v[204:207], v[48:51]
	v_mfma_f32_16x16x32_bf16 v[36:39], v[188:191], v[218:221], v[36:39]
	v_mfma_f32_16x16x32_bf16 v[32:35], v[196:199], v[218:221], v[32:35]
	v_mfma_f32_16x16x32_bf16 v[20:23], v[188:191], v[226:229], v[20:23]
	v_mfma_f32_16x16x32_bf16 v[16:19], v[196:199], v[226:229], v[16:19]
	v_mfma_f32_16x16x32_bf16 v[4:7], v[188:191], v[234:237], v[4:7]
	v_mfma_f32_16x16x32_bf16 v[0:3], v[196:199], v[234:237], v[0:3]
	s_setprio 0
	s_barrier
	s_add_u32 s82, s82, 0x100
	s_addc_u32 s83, s83, 0
	s_add_u32 s81, s81, 0x100
	s_addc_u32 s91, s91, 0
	s_cmp_ge_u32 s98, s60
	s_cbranch_scc1 .LBB0_107
